# pass2 T layout: transposed cumsum / outputs (swapped MFMA operands), 8-byte LDS accesses in prepare/norm, permlane-swap sums of squares; replaces p2_ssq/p2_norm2/p2_prep, keeps shared-Qb step (2)+(3)
# speedup vs baseline: 1.0155x; 1.0103x over previous
.LBB0_1323:
	s_movk_i32 s68, 0x1000
	s_or_b64 exec, exec, s[0:1]
	v_readlane_b32 s0, v253, 17
	v_readlane_b32 s1, v253, 18
	s_and_b64 vcc, exec, s[0:1]
	s_waitcnt lgkmcnt(0)
	s_barrier
	v_mbcnt_lo_u32_b32 v17, -1, 0
	v_mbcnt_hi_u32_b32 v17, -1, v17
	v_lshl_or_b32 v17, s66, 6, v17
	s_cbranch_vccnz .LBB0_1353
	v_ashrrev_i32_e32 v74, 4, v17
	s_movk_i32 s0, 0x110
	v_mul_lo_u32 v93, v74, s0
	v_and_b32_e32 v77, 63, v17
	v_add_u32_e32 v76, 0, v93
	v_mad_u64_u32 v[78:79], s[0:1], v74, 48, v[76:77]
	s_movk_i32 s0, 0xffd0
	s_waitcnt vmcnt(12)
	v_mad_u64_u32 v[8:9], s[0:1], v74, s0, v[78:79]
	s_waitcnt vmcnt(9)
	v_bfe_u32 v0, v17, 1, 5
	v_and_b32_e32 v95, 15, v17
	v_and_b32_e32 v2, 24, v0
	v_lshrrev_b32_e32 v9, 2, v95
	s_movk_i32 s2, 0x140
	v_or_b32_e32 v1, v2, v9
	v_mul_u32_u24_e32 v96, 0x140, v1
	v_mad_u32_u24 v97, v1, s2, 0
	v_cmp_gt_u32_e32 vcc, v2, v95
	v_or_b32_e32 v1, 2, v2
	v_or_b32_e32 v13, 7, v0
	v_cndmask_b32_e64 v3, v234, 0, vcc
	v_cmp_lt_u32_e32 vcc, v95, v1
	v_or_b32_e32 v12, 16, v95
	v_or_b32_e32 v4, 3, v2
	v_cndmask_b32_e64 v5, v234, 0, vcc
	v_cmp_lt_u32_e32 vcc, v2, v95
	s_mov_b32 s0, 0x5040100
	v_or_b32_e32 v14, 6, v2
	v_cndmask_b32_e32 v6, 0, v234, vcc
	v_cmp_gt_u32_e32 vcc, v13, v95
	v_bfe_u32 v11, v17, 4, 2
	v_readlane_b32 s18, v252, 21
	v_cndmask_b32_e64 v7, v234, 0, vcc
	v_cmp_gt_u32_e32 vcc, v2, v12
	v_lshlrev_b32_e32 v80, 4, v95
	v_mov_b32_e32 v81, v16
	v_cndmask_b32_e64 v0, v234, 0, vcc
	v_cmp_lt_u32_e32 vcc, v2, v12
	v_readlane_b32 s19, v252, 22
	v_lshlrev_b32_e32 v92, 2, v77
	v_cndmask_b32_e32 v15, 0, v234, vcc
	v_cmp_gt_u32_e32 vcc, v1, v12
	v_perm_b32 v0, v15, v0, s0
	v_lshl_add_u64 v[82:83], s[18:19], 0, v[80:81]
	v_cndmask_b32_e64 v1, v234, 0, vcc
	v_cmp_gt_u32_e32 vcc, v4, v12
	v_readlane_b32 s18, v252, 23
	v_lshlrev_b32_e32 v10, 3, v95
	v_cndmask_b32_e64 v15, v234, 0, vcc
	v_perm_b32 v1, v15, v1, s0
	v_or_b32_e32 v15, 5, v2
	v_or_b32_e32 v2, 4, v2
	v_cmp_gt_u32_e32 vcc, v4, v95
	v_perm_b32 v4, v6, v3, s0
	s_waitcnt vmcnt(2)
	v_lshlrev_b32_e32 v112, 7, v11
	v_cndmask_b32_e64 v18, v234, 0, vcc
	v_cmp_gt_u32_e32 vcc, v2, v95
	v_perm_b32 v5, v18, v5, s0
	v_readlane_b32 s19, v252, 24
	v_cndmask_b32_e64 v19, v234, 0, vcc
	v_cmp_gt_u32_e32 vcc, v15, v95
	v_ashrrev_i32_e32 v75, 31, v74
	v_mul_lo_u32 v94, v74, s2
	v_cndmask_b32_e64 v20, v234, 0, vcc
	v_cmp_gt_u32_e32 vcc, v14, v95
	v_perm_b32 v6, v20, v19, s0
	v_and_b32_e32 v79, 12, v92
	v_cndmask_b32_e64 v21, v234, 0, vcc
	v_cmp_gt_u32_e32 vcc, v2, v12
	v_perm_b32 v7, v7, v21, s0
	v_lshlrev_b32_e32 v104, 3, v11
	v_cndmask_b32_e64 v2, v234, 0, vcc
	v_cmp_gt_u32_e32 vcc, v15, v12
	v_and_b32_e32 v105, 48, v17
	v_cmp_eq_u32_e64 s[2:3], 15, v95
	v_cndmask_b32_e64 v3, v234, 0, vcc
	v_cmp_gt_u32_e32 vcc, v14, v12
	v_perm_b32 v2, v3, v2, s0
	s_waitcnt vmcnt(0)
	v_mul_u32_u24_e32 v109, 0x110, v95
	v_cndmask_b32_e64 v3, v234, 0, vcc
	v_cmp_gt_u32_e32 vcc, v13, v12
	v_or_b32_e32 v113, 32, v112
	v_mul_u32_u24_e32 v119, 0x440, v11
	v_cndmask_b32_e64 v13, v234, 0, vcc
	v_perm_b32 v3, v13, v3, s0
	v_bfe_u32 v13, v17, 2, 4
	v_and_b32_e32 v14, 12, v13
	v_mul_u32_u24_e32 v98, 0x140, v14
	v_mul_u32_u24_e32 v99, 0x110, v14
	v_or_b32_e32 v14, 3, v13
	v_or_b32_e32 v13, 19, v13
	v_mul_u32_u24_e32 v102, 0x140, v13
	v_mul_u32_u24_e32 v103, 0x110, v13
	v_lshlrev_b32_e32 v13, 2, v11
	v_or_b32_e32 v9, v13, v9
	v_mul_u32_u24_e32 v106, 0x140, v9
	v_lshlrev_b32_e32 v9, 2, v17
	v_mul_u32_u24_e32 v100, 0x140, v14
	v_mul_u32_u24_e32 v101, 0x110, v14
	v_and_b32_e32 v107, 12, v9
	v_or_b32_e32 v9, 16, v13
	v_cmp_gt_u32_e64 s[4:5], v13, v95
	v_cmp_lt_u32_e64 s[6:7], v13, v95
	v_or_b32_e32 v14, 2, v13
	v_or_b32_e32 v15, 3, v13
	v_or_b32_e32 v18, 17, v13
	v_or_b32_e32 v19, 18, v13
	v_or_b32_e32 v13, 19, v13
	v_cmp_gt_u32_e64 s[0:1], 16, v77
	v_lshlrev_b32_e32 v108, 5, v9
	v_cmp_gt_u32_e64 s[8:9], v14, v95
	v_cmp_gt_u32_e64 s[10:11], v15, v95
	v_cmp_gt_u32_e64 s[12:13], v18, v12
	v_cmp_gt_u32_e64 s[14:15], v19, v12
	v_cmp_gt_u32_e64 s[16:17], v13, v12
	v_lshlrev_b32_e32 v110, 1, v107
	v_lshlrev_b32_e32 v111, 2, v9
	v_lshlrev_b32_e32 v114, 5, v14
	v_lshlrev_b32_e32 v115, 5, v15
	v_lshlrev_b32_e32 v116, 5, v18
	v_lshlrev_b32_e32 v117, 5, v19
	v_lshlrev_b32_e32 v118, 5, v13
	v_lshl_add_u64 v[84:85], s[18:19], 0, v[80:81]
	v_lshlrev_b32_e32 v86, 1, v10
	v_add_u32_e32 v81, v8, v80
	v_readlane_b32 s24, v248, 36
	v_readlane_b32 s25, v251, 49
	v_readlane_b32 s18, v248, 5
	v_readlane_b32 s19, v248, 6
	s_branch .LBB0_1326

.LBB0_1328:
	s_or_b64 exec, exec, s[22:23]
	s_lshl_b32 s19, s24, 1
	s_and_b32 s22, s25, 0xf00
	s_and_b32 s23, s19, 0x300
	s_lshl_b32 s19, s26, 2
	s_add_u32 s20, s22, s20
	v_or_b32_e32 v60, s27, v107
	s_addc_u32 s21, 0, s21
	v_mov_b32_e32 v58, s23
	v_mov_b32_e32 v59, v16
	v_lshlrev_b32_e32 v123, 1, v60
	v_lshl_add_u64 v[60:61], s[20:21], 0, v[74:75]
	s_movk_i32 s22, 0x1600
	s_waitcnt lgkmcnt(0)
	s_barrier
	v_lshlrev_b64 v[62:63], 11, v[60:61]
	v_mad_u64_u32 v[58:59], s[20:21], v60, s22, v[58:59]
	v_or_b32_e32 v62, s23, v62
	v_mad_i32_i24 v59, v61, s22, v59
	s_waitcnt vmcnt(12)
	v_lshlrev_b32_e32 v26, 16, v38
	v_and_b32_e32 v27, 0xffff0000, v38
	v_lshlrev_b32_e32 v28, 16, v39
	v_and_b32_e32 v29, 0xffff0000, v39
	s_waitcnt vmcnt(11)
	v_lshlrev_b32_e32 v30, 16, v34
	v_and_b32_e32 v31, 0xffff0000, v34
	v_lshlrev_b32_e32 v32, 16, v35
	v_and_b32_e32 v33, 0xffff0000, v35
	s_waitcnt vmcnt(10)
	v_lshlrev_b32_e32 v34, 16, v36
	v_and_b32_e32 v35, 0xffff0000, v36
	v_lshlrev_b32_e32 v36, 16, v37
	v_and_b32_e32 v37, 0xffff0000, v37
	s_waitcnt vmcnt(9)
	v_lshlrev_b32_e32 v38, 16, v40
	v_and_b32_e32 v39, 0xffff0000, v40
	v_lshlrev_b32_e32 v40, 16, v41
	v_and_b32_e32 v41, 0xffff0000, v41
	s_waitcnt vmcnt(8)
	v_lshlrev_b32_e32 v42, 16, v44
	v_and_b32_e32 v43, 0xffff0000, v44
	v_lshlrev_b32_e32 v44, 16, v45
	v_and_b32_e32 v45, 0xffff0000, v45
	s_waitcnt vmcnt(7)
	v_lshlrev_b32_e32 v46, 16, v48
	v_and_b32_e32 v47, 0xffff0000, v48
	v_lshlrev_b32_e32 v48, 16, v49
	v_and_b32_e32 v49, 0xffff0000, v49
	s_waitcnt vmcnt(6)
	v_lshlrev_b32_e32 v50, 16, v52
	v_and_b32_e32 v51, 0xffff0000, v52
	v_lshlrev_b32_e32 v52, 16, v53
	v_and_b32_e32 v53, 0xffff0000, v53
	s_waitcnt vmcnt(5)
	v_lshlrev_b32_e32 v54, 16, v56
	v_and_b32_e32 v55, 0xffff0000, v56
	v_lshlrev_b32_e32 v56, 16, v57
	v_and_b32_e32 v57, 0xffff0000, v57
	v_add_lshl_u32 v124, s27, v77, 2
	v_lshl_or_b32 v222, s27, 1, v104
	v_mul_u32_u24_e32 v236, 0x140, v95
	v_lshlrev_b32_e32 v224, 1, v222
	v_add_u32_e32 v236, v236, v222
	global_load_dwordx4 v[224:227], v224, s[70:71]
	v_lshl_add_u64 v[88:89], v[82:83], 0, v[62:63]
	v_lshl_add_u64 v[90:91], v[84:85], 0, v[58:59]
	s_mov_b32 s26, 0
	s_branch .LBB0_1331

.LBB0_1330:
	s_add_i32 s26, s26, 1
	s_mov_b64 s[20:21], 0x10000
	v_lshl_add_u32 v160, v95, 5, s27
	ds_read_b128 v[148:151], v160 offset:57344
	ds_read_b128 v[152:155], v160 offset:57360
	ds_read_b128 v[156:159], v160 offset:57856
	ds_read_b128 v[162:165], v160 offset:57872
	v_add3_u32 v125, s27, v109, v222
	ds_read_b64 v[166:167], v125 offset:48128
	ds_read_b64 v[168:169], v125 offset:52480
	s_waitcnt vmcnt(4)
	s_waitcnt lgkmcnt(4)
	v_add_f32_e32 v170, v148, v149
	v_add_f32_e32 v171, v150, v151
	v_add_f32_e32 v172, v152, v153
	v_add_f32_e32 v170, v170, v171
	v_add_f32_e32 v173, v154, v155
	v_add_f32_e32 v172, v172, v173
	v_add_f32_e32 v170, v170, v172
	v_fmamk_f32 v170, v170, 0x3c000000, v218
	v_rsq_f32_e32 v170, v170
	s_waitcnt lgkmcnt(2)
	v_add_f32_e32 v174, v156, v157
	v_add_f32_e32 v175, v158, v159
	v_add_f32_e32 v176, v162, v163
	v_add_f32_e32 v174, v174, v175
	v_add_f32_e32 v177, v164, v165
	v_add_f32_e32 v176, v176, v177
	v_add_f32_e32 v174, v174, v176
	v_fmamk_f32 v174, v174, 0x3c000000, v218
	v_rsq_f32_e32 v174, v174
	s_waitcnt lgkmcnt(0)
	v_lshlrev_b32_e32 v178, 16, v166
	v_and_b32_e32 v179, 0xffff0000, v166
	v_lshlrev_b32_e32 v200, 16, v167
	v_and_b32_e32 v201, 0xffff0000, v167
	v_lshlrev_b32_e32 v202, 16, v168
	v_and_b32_e32 v203, 0xffff0000, v168
	v_lshlrev_b32_e32 v204, 16, v169
	v_and_b32_e32 v205, 0xffff0000, v169
	v_mul_f32_e32 v206, v62, v170
	v_mul_f32_e32 v207, v63, v170
	v_mul_f32_e32 v208, v64, v170
	v_mul_f32_e32 v209, v65, v170
	v_mul_f32_e32 v210, v58, v174
	v_mul_f32_e32 v211, v59, v174
	v_mul_f32_e32 v212, v60, v174
	v_mul_f32_e32 v213, v61, v174
	v_mul_f32_e32 v206, v224, v206
	v_mul_f32_e32 v207, v225, v207
	v_mul_f32_e32 v208, v226, v208
	v_mul_f32_e32 v209, v227, v209
	v_mul_f32_e32 v210, v224, v210
	v_mul_f32_e32 v211, v225, v211
	v_mul_f32_e32 v212, v226, v212
	v_mul_f32_e32 v213, v227, v213
	v_mul_f32_e32 v206, v206, v178
	v_mul_f32_e32 v207, v207, v179
	v_mul_f32_e32 v208, v208, v200
	v_mul_f32_e32 v209, v209, v201
	v_mul_f32_e32 v210, v210, v202
	v_mul_f32_e32 v211, v211, v203
	v_mul_f32_e32 v212, v212, v204
	v_mul_f32_e32 v213, v213, v205
	v_cvt_pk_bf16_f32 v148, v206, v207
	v_cvt_pk_bf16_f32 v149, v208, v209
	v_cvt_pk_bf16_f32 v150, v210, v211
	v_cvt_pk_bf16_f32 v151, v212, v213
	ds_write_b64 v125, v[148:149] offset:8704
	ds_write_b64 v125, v[150:151] offset:13056
	s_cmp_lg_u32 s26, 8
	s_waitcnt lgkmcnt(0)
	s_barrier
	v_add3_u32 v58, s27, v93, v80
	ds_read_b128 v[58:61], v58 offset:8704
	s_waitcnt lgkmcnt(0)
	global_store_dwordx4 v[88:89], v[58:61], off
	v_lshl_add_u64 v[88:89], v[88:89], 0, s[20:21]
	s_mov_b64 s[20:21], 0x2c000
	v_lshl_add_u64 v[90:91], v[90:91], 0, s[20:21]
	s_cbranch_scc0 .LBB0_1325

.LBB0_1334:
	s_mul_i32 s22, s22, 0xe400
	s_add_i32 s27, s22, 0
	v_add3_u32 v147, s27, v104, v109
	s_add_i32 s29, s27, s19
	ds_read_b64 v[148:149], v147
	ds_read_b64 v[150:151], v147 offset:32
	ds_read_b64 v[152:153], v147 offset:4352
	ds_read_b64 v[154:155], v147 offset:4384
	ds_read_b64 v[196:197], v147 offset:8704
	ds_read_b64 v[198:199], v147 offset:8736
	ds_read_b64 v[200:201], v147 offset:13056
	ds_read_b64 v[202:203], v147 offset:13088
	v_cvt_pk_bf16_f32 v126, v26, v27
	v_cvt_pk_bf16_f32 v127, v28, v29
	v_cvt_pk_bf16_f32 v128, v30, v31
	v_cvt_pk_bf16_f32 v129, v32, v33
	ds_read_b64 v[156:157], v147 offset:64
	ds_read_b64 v[158:159], v147 offset:96
	ds_read_b64 v[160:161], v147 offset:4416
	ds_read_b64 v[162:163], v147 offset:4448
	ds_read_b64 v[204:205], v147 offset:8768
	ds_read_b64 v[206:207], v147 offset:8800
	s_waitcnt lgkmcnt(12)
	v_mfma_f32_16x16x32_bf16 v[62:65], v[126:129], v[148:151], 0
	ds_read_b64 v[208:209], v147 offset:13120
	ds_read_b64 v[210:211], v147 offset:13152
	v_cvt_pk_bf16_f32 v130, v34, v35
	v_cvt_pk_bf16_f32 v131, v36, v37
	v_cvt_pk_bf16_f32 v132, v38, v39
	v_cvt_pk_bf16_f32 v133, v40, v41
	s_waitcnt lgkmcnt(12)
	v_mfma_f32_16x16x32_bf16 v[58:61], v[126:129], v[152:155], 0
	s_waitcnt lgkmcnt(10)
	v_mfma_f32_16x16x32_bf16 v[164:167], v[196:199], v[148:151], 0
	v_mfma_f32_16x16x32_bf16 v[168:171], v[196:199], v[152:155], 0
	s_waitcnt lgkmcnt(8)
	v_mfma_f32_16x16x32_bf16 v[172:175], v[200:203], v[152:155], 0
	ds_read_b64 v[148:149], v147 offset:128
	ds_read_b64 v[150:151], v147 offset:160
	ds_read_b64 v[152:153], v147 offset:4480
	ds_read_b64 v[154:155], v147 offset:4512
	ds_read_b64 v[196:197], v147 offset:8832
	ds_read_b64 v[198:199], v147 offset:8864
	s_waitcnt lgkmcnt(12)
	v_mfma_f32_16x16x32_bf16 v[62:65], v[130:133], v[156:159], v[62:65]
	ds_read_b64 v[200:201], v147 offset:13184
	ds_read_b64 v[202:203], v147 offset:13216
	v_cvt_pk_bf16_f32 v134, v42, v43
	v_cvt_pk_bf16_f32 v135, v44, v45
	v_cvt_pk_bf16_f32 v136, v46, v47
	v_cvt_pk_bf16_f32 v137, v48, v49
	s_waitcnt lgkmcnt(12)
	v_mfma_f32_16x16x32_bf16 v[58:61], v[130:133], v[160:163], v[58:61]
	s_waitcnt lgkmcnt(10)
	v_mfma_f32_16x16x32_bf16 v[164:167], v[204:207], v[156:159], v[164:167]
	v_mfma_f32_16x16x32_bf16 v[168:171], v[204:207], v[160:163], v[168:171]
	s_waitcnt lgkmcnt(8)
	v_mfma_f32_16x16x32_bf16 v[172:175], v[208:211], v[160:163], v[172:175]
	ds_read_b64 v[156:157], v147 offset:192
	ds_read_b64 v[158:159], v147 offset:224
	ds_read_b64 v[160:161], v147 offset:4544
	ds_read_b64 v[162:163], v147 offset:4576
	ds_read_b64 v[204:205], v147 offset:8896
	ds_read_b64 v[206:207], v147 offset:8928
	s_waitcnt lgkmcnt(12)
	v_mfma_f32_16x16x32_bf16 v[62:65], v[134:137], v[148:151], v[62:65]
	ds_read_b64 v[208:209], v147 offset:13248
	ds_read_b64 v[210:211], v147 offset:13280
	v_cvt_pk_bf16_f32 v138, v50, v51
	v_cvt_pk_bf16_f32 v139, v52, v53
	v_cvt_pk_bf16_f32 v140, v54, v55
	v_cvt_pk_bf16_f32 v141, v56, v57
	s_waitcnt lgkmcnt(12)
	v_mfma_f32_16x16x32_bf16 v[58:61], v[134:137], v[152:155], v[58:61]
	s_waitcnt lgkmcnt(10)
	v_mfma_f32_16x16x32_bf16 v[164:167], v[196:199], v[148:151], v[164:167]
	v_mfma_f32_16x16x32_bf16 v[168:171], v[196:199], v[152:155], v[168:171]
	s_waitcnt lgkmcnt(8)
	v_mfma_f32_16x16x32_bf16 v[172:175], v[200:203], v[152:155], v[172:175]
	v_add_u32_e32 v176, s27, v106
	v_add_u32_e32 v68, v176, v123
	ds_read_b64_tr_b16 v[66:67], v68 offset:37888
	ds_read_b64_tr_b16 v[68:69], v68 offset:43008
	s_waitcnt lgkmcnt(8)
	v_mfma_f32_16x16x32_bf16 v[62:65], v[138:141], v[156:159], v[62:65]
	s_waitcnt lgkmcnt(6)
	v_mfma_f32_16x16x32_bf16 v[58:61], v[138:141], v[160:163], v[58:61]
	s_waitcnt lgkmcnt(4)
	v_mfma_f32_16x16x32_bf16 v[164:167], v[204:207], v[156:159], v[164:167]
	v_mfma_f32_16x16x32_bf16 v[168:171], v[204:207], v[160:163], v[168:171]
	s_waitcnt lgkmcnt(2)
	v_mfma_f32_16x16x32_bf16 v[172:175], v[208:211], v[160:163], v[172:175]
	v_add_u32_e32 v125, s27, v105
	v_add_u32_e32 v134, v176, v110
	v_mov_b32_e32 v177, s55
	v_mov_b32_e32 v72, v16
	v_mov_b32_e32 v73, v16
	s_nop 0
	v_cndmask_b32_e64 v165, 0, v165, s[6:7]
	v_cndmask_b32_e64 v166, v166, 0, s[8:9]
	v_cndmask_b32_e64 v167, v167, 0, s[10:11]
	v_cndmask_b32_e64 v164, v164, v177, s[4:5]
	v_cvt_pk_bf16_f32 v70, v164, v165
	v_cvt_pk_bf16_f32 v71, v166, v167
	v_cndmask_b32_e64 v172, v172, v177, s[4:5]
	v_cndmask_b32_e64 v173, v173, 0, s[12:13]
	v_cndmask_b32_e64 v174, v174, 0, s[14:15]
	v_cndmask_b32_e64 v175, v175, 0, s[16:17]
	s_waitcnt lgkmcnt(0)
	v_mfma_f32_16x16x32_bf16 v[62:65], v[66:69], v[70:73], v[62:65]
	v_cvt_pk_bf16_f32 v70, v168, v169
	v_cvt_pk_bf16_f32 v71, v170, v171
	v_cvt_pk_bf16_f32 v72, v172, v173
	v_cvt_pk_bf16_f32 v73, v174, v175
	s_nop 1
	v_mfma_f32_16x16x32_bf16 v[58:61], v[66:69], v[70:73], v[58:61]
	ds_read_b128 v[70:73], v125 offset:56832
	ds_read_b64_tr_b16 v[128:129], v134 offset:32768
	ds_read_b64_tr_b16 v[126:127], v134 offset:27648
	ds_read_b64_tr_b16 v[130:131], v134 offset:27680
	s_waitcnt lgkmcnt(3)
	v_pk_mul_f32 v[26:27], v[26:27], v[70:71]
	v_add_u32_e32 v70, s27, v111
	v_pk_mul_f32 v[28:29], v[28:29], v[72:73]
	ds_read_b128 v[70:73], v70 offset:56832
	ds_read_b64_tr_b16 v[132:133], v134 offset:32800
	s_waitcnt lgkmcnt(3)
	v_mfma_f32_16x16x32_bf16 v[26:29], v[126:129], v[66:69], v[26:29]
	s_waitcnt lgkmcnt(1)
	v_pk_mul_f32 v[32:33], v[32:33], v[72:73]
	v_pk_mul_f32 v[30:31], v[30:31], v[70:71]
	ds_read_b128 v[70:73], v125 offset:56960
	ds_read_b64_tr_b16 v[126:127], v134 offset:27712
	ds_read_b64_tr_b16 v[128:129], v134 offset:32832
	s_waitcnt lgkmcnt(3)
	v_mfma_f32_16x16x32_bf16 v[30:33], v[130:133], v[66:69], v[30:33]
	s_waitcnt lgkmcnt(2)
	v_pk_mul_f32 v[36:37], v[36:37], v[72:73]
	v_pk_mul_f32 v[34:35], v[34:35], v[70:71]
	s_waitcnt lgkmcnt(0)
	s_nop 0
	v_mfma_f32_16x16x32_bf16 v[34:37], v[126:129], v[66:69], v[34:37]
	ds_read_b128 v[70:73], v125 offset:57024
	ds_read_b64_tr_b16 v[126:127], v134 offset:27744
	ds_read_b64_tr_b16 v[128:129], v134 offset:32864
	s_waitcnt lgkmcnt(2)
	v_pk_mul_f32 v[40:41], v[40:41], v[72:73]
	v_pk_mul_f32 v[38:39], v[38:39], v[70:71]
	s_waitcnt lgkmcnt(0)
	s_nop 0
	v_mfma_f32_16x16x32_bf16 v[38:41], v[126:129], v[66:69], v[38:41]
	ds_read_b128 v[70:73], v125 offset:57088
	ds_read_b64_tr_b16 v[126:127], v134 offset:27776
	ds_read_b64_tr_b16 v[128:129], v134 offset:32896
	s_waitcnt lgkmcnt(2)
	v_pk_mul_f32 v[44:45], v[44:45], v[72:73]
	v_pk_mul_f32 v[42:43], v[42:43], v[70:71]
	s_waitcnt lgkmcnt(0)
	s_nop 0
	v_mfma_f32_16x16x32_bf16 v[42:45], v[126:129], v[66:69], v[42:45]
	ds_read_b128 v[70:73], v125 offset:57152
	ds_read_b64_tr_b16 v[126:127], v134 offset:27808
	ds_read_b64_tr_b16 v[128:129], v134 offset:32928
	s_waitcnt lgkmcnt(2)
	v_pk_mul_f32 v[48:49], v[48:49], v[72:73]
	v_pk_mul_f32 v[46:47], v[46:47], v[70:71]
	s_waitcnt lgkmcnt(0)
	s_nop 0
	v_mfma_f32_16x16x32_bf16 v[46:49], v[126:129], v[66:69], v[46:49]
	ds_read_b128 v[70:73], v125 offset:57216
	ds_read_b64_tr_b16 v[126:127], v134 offset:27840
	ds_read_b64_tr_b16 v[128:129], v134 offset:32960
	s_waitcnt lgkmcnt(2)
	v_pk_mul_f32 v[52:53], v[52:53], v[72:73]
	v_pk_mul_f32 v[50:51], v[50:51], v[70:71]
	s_waitcnt lgkmcnt(0)
	s_nop 0
	v_mfma_f32_16x16x32_bf16 v[50:53], v[126:129], v[66:69], v[50:53]
	ds_read_b128 v[70:73], v125 offset:57280
	ds_read_b64_tr_b16 v[126:127], v134 offset:27872
	ds_read_b64_tr_b16 v[128:129], v134 offset:32992
	s_waitcnt lgkmcnt(2)
	v_pk_mul_f32 v[56:57], v[56:57], v[72:73]
	v_pk_mul_f32 v[54:55], v[54:55], v[70:71]
	s_waitcnt lgkmcnt(0)
	s_nop 0
	v_mfma_f32_16x16x32_bf16 v[54:57], v[126:129], v[66:69], v[54:57]
	v_mul_f32_e32 v148, v62, v62
	v_mul_f32_e32 v149, v58, v58
	v_fmac_f32_e32 v148, v63, v63
	v_fmac_f32_e32 v149, v59, v59
	v_fmac_f32_e32 v148, v64, v64
	v_fmac_f32_e32 v149, v60, v60
	v_fmac_f32_e32 v148, v65, v65
	v_fmac_f32_e32 v149, v61, v61
	v_lshl_add_u32 v156, v77, 5, s29
	s_nop 0
	v_permlane16_swap_b32_e32 v148, v149
	v_add_f32_e32 v148, v148, v149
	v_mov_b32_e32 v149, v148
	s_nop 1
	v_permlane32_swap_b32_e32 v148, v149
	v_add_f32_e32 v148, v148, v149
	s_mov_b64 s[22:23], exec
	s_mov_b32 exec_hi, 0
	ds_write_b32 v156, v148 offset:57344
	s_mov_b64 exec, s[22:23]
	s_waitcnt lgkmcnt(0)
	s_barrier
	s_andn2_b64 vcc, exec, s[20:21]
	s_cbranch_vccnz .LBB0_1330
	v_add3_u32 v68, s28, v96, v120
	ds_read_b64_tr_b16 v[66:67], v68 offset:17408
	ds_read_b64_tr_b16 v[68:69], v68 offset:18688
	v_add_u32_e32 v138, s28, v236
	v_add3_u32 v139, s28, v109, v222
	ds_read_b64 v[180:181], v138 offset:17408
	ds_read_b64 v[182:183], v138 offset:22528
	ds_read_b64 v[184:185], v139
	ds_read_b64 v[186:187], v139 offset:4352
	s_waitcnt lgkmcnt(4)
	v_mfma_f32_16x16x32_bf16 v[70:73], v[66:69], v[4:7], 0
	v_mfma_f32_16x16x32_bf16 v[66:69], v[66:69], v[0:3], 0
	s_mov_b32 s23, 0x42e60000
	s_waitcnt lgkmcnt(0)
	v_lshlrev_b32_e32 v188, 16, v180
	v_and_b32_e32 v189, 0xffff0000, v180
	v_lshlrev_b32_e32 v190, 16, v181
	v_and_b32_e32 v191, 0xffff0000, v181
	v_lshlrev_b32_e32 v192, 16, v182
	v_and_b32_e32 v193, 0xffff0000, v182
	v_lshlrev_b32_e32 v194, 16, v183
	v_and_b32_e32 v195, 0xffff0000, v183
	v_lshlrev_b32_e32 v196, 16, v184
	v_and_b32_e32 v197, 0xffff0000, v184
	v_lshlrev_b32_e32 v198, 16, v185
	v_and_b32_e32 v199, 0xffff0000, v185
	v_lshlrev_b32_e32 v200, 16, v186
	v_and_b32_e32 v201, 0xffff0000, v186
	v_lshlrev_b32_e32 v202, 16, v187
	v_and_b32_e32 v203, 0xffff0000, v187
	v_exp_f32_e32 v188, v188
	v_exp_f32_e32 v189, v189
	v_exp_f32_e32 v190, v190
	v_exp_f32_e32 v191, v191
	v_exp_f32_e32 v192, v192
	v_exp_f32_e32 v193, v193
	v_exp_f32_e32 v194, v194
	v_exp_f32_e32 v195, v195
	v_sub_f32_e32 v188, 1.0, v188
	v_sub_f32_e32 v189, 1.0, v189
	v_sub_f32_e32 v190, 1.0, v190
	v_sub_f32_e32 v191, 1.0, v191
	v_sub_f32_e32 v192, 1.0, v192
	v_sub_f32_e32 v193, 1.0, v193
	v_sub_f32_e32 v194, 1.0, v194
	v_sub_f32_e32 v195, 1.0, v195
	v_exp_f32_e32 v204, v70
	v_exp_f32_e32 v205, v71
	v_exp_f32_e32 v206, v72
	v_exp_f32_e32 v207, v73
	v_exp_f32_e32 v208, v66
	v_exp_f32_e32 v209, v67
	v_exp_f32_e32 v210, v68
	v_exp_f32_e32 v211, v69
	v_sub_f32_dpp v126, v66, v70 row_newbcast:15 row_mask:0xf bank_mask:0xf
	v_sub_f32_dpp v127, v67, v71 row_newbcast:15 row_mask:0xf bank_mask:0xf
	v_sub_f32_dpp v128, v68, v72 row_newbcast:15 row_mask:0xf bank_mask:0xf
	v_sub_f32_dpp v129, v69, v73 row_newbcast:15 row_mask:0xf bank_mask:0xf
	v_sub_f32_dpp v130, v66, v66 row_newbcast:15 row_mask:0xf bank_mask:0xf
	v_sub_f32_dpp v131, v67, v67 row_newbcast:15 row_mask:0xf bank_mask:0xf
	v_sub_f32_dpp v132, v68, v68 row_newbcast:15 row_mask:0xf bank_mask:0xf
	v_sub_f32_dpp v133, v69, v69 row_newbcast:15 row_mask:0xf bank_mask:0xf
	v_mul_f32_e32 v196, v196, v204
	v_mul_f32_e32 v197, v197, v205
	v_mul_f32_e32 v198, v198, v206
	v_mul_f32_e32 v199, v199, v207
	v_mul_f32_e32 v200, v200, v208
	v_mul_f32_e32 v201, v201, v209
	v_mul_f32_e32 v202, v202, v210
	v_mul_f32_e32 v203, v203, v211
	v_min_f32_e64 v204, -v70, s23
	v_min_f32_e64 v205, -v71, s23
	v_min_f32_e64 v206, -v72, s23
	v_min_f32_e64 v207, -v73, s23
	v_min_f32_e64 v208, -v66, s23
	v_min_f32_e64 v209, -v67, s23
	v_min_f32_e64 v210, -v68, s23
	v_min_f32_e64 v211, -v69, s23
	v_exp_f32_e32 v126, v126
	v_exp_f32_e32 v127, v127
	v_exp_f32_e32 v128, v128
	v_exp_f32_e32 v129, v129
	v_exp_f32_e32 v130, v130
	v_exp_f32_e32 v131, v131
	v_exp_f32_e32 v132, v132
	v_exp_f32_e32 v133, v133
	v_exp_f32_e32 v204, v204
	v_exp_f32_e32 v205, v205
	v_exp_f32_e32 v206, v206
	v_exp_f32_e32 v207, v207
	v_exp_f32_e32 v208, v208
	v_exp_f32_e32 v209, v209
	v_exp_f32_e32 v210, v210
	v_exp_f32_e32 v211, v211
	v_exp_f32_e32 v212, v66
	v_exp_f32_e32 v213, v67
	v_exp_f32_e32 v214, v68
	v_exp_f32_e32 v215, v69
	v_mul_f32_e32 v126, v126, v188
	v_mul_f32_e32 v127, v127, v189
	v_mul_f32_e32 v128, v128, v190
	v_mul_f32_e32 v129, v129, v191
	v_mul_f32_e32 v130, v130, v192
	v_mul_f32_e32 v131, v131, v193
	v_mul_f32_e32 v132, v132, v194
	v_mul_f32_e32 v133, v133, v195
	v_mul_f32_e32 v204, v204, v188
	v_mul_f32_e32 v205, v205, v189
	v_mul_f32_e32 v206, v206, v190
	v_mul_f32_e32 v207, v207, v191
	v_mul_f32_e32 v208, v208, v192
	v_mul_f32_e32 v209, v209, v193
	v_mul_f32_e32 v210, v210, v194
	v_mul_f32_e32 v211, v211, v195
	v_lshl_add_u32 v216, v222, 1, s28
	v_cvt_pk_bf16_f32 v180, v196, v197
	v_cvt_pk_bf16_f32 v181, v198, v199
	v_cvt_pk_bf16_f32 v182, v200, v201
	v_cvt_pk_bf16_f32 v183, v202, v203
	v_cvt_pk_bf16_f32 v184, v204, v205
	v_cvt_pk_bf16_f32 v185, v206, v207
	v_cvt_pk_bf16_f32 v186, v208, v209
	v_cvt_pk_bf16_f32 v187, v210, v211
	v_cvt_pk_bf16_f32 v134, v126, v127
	v_cvt_pk_bf16_f32 v135, v128, v129
	v_cvt_pk_bf16_f32 v136, v130, v131
	v_cvt_pk_bf16_f32 v137, v132, v133
	ds_write_b64 v139, v[180:181]
	ds_write_b64 v139, v[182:183] offset:4352
	ds_write_b64 v139, v[184:185] offset:8704
	ds_write_b64 v139, v[186:187] offset:13056
	ds_write_b64 v138, v[134:135] offset:27648
	ds_write_b64 v138, v[136:137] offset:32768
	s_and_saveexec_b64 s[20:21], s[2:3]
	ds_write_b128 v216, v[212:215] offset:56832
	s_branch .LBB0_1329
